# GEMM k-loop specialised per ping-pong half: leading half waits for its LDS-DMA after the MFMA segment (before the second barrier) instead of before the first
# baseline (speedup 1.0000x reference)
; #define PG8_STAGE(bufoff, gbase, voff) do { _Pragma("unroll") for (int _i = 0; _i < 2; ++_i) \
;         __builtin_amdgcn_global_load_lds((const unsigned*)((const char*)(gbase) + (voff)[_i]), (LAS unsigned*)(lds + (bufoff) + ldsw + _i * 8192), 16, 0, 0); } while (0)
; #define PG8_LDA(dst, b, h) do { _Pragma("unroll") for (int m = 0; m < 4; ++m) _Pragma("unroll") for (int k = 0; k < 2; ++k) dst[m][k] = *(const LAS bf16x8*)(lds + PG8_SA(b, h) + aoff + m * 2048 + k * 1024); } while (0)
; #define PG8_LDB(dst, b, h) do { _Pragma("unroll") for (int n = 0; n < 2; ++n) _Pragma("unroll") for (int k = 0; k < 2; ++k) dst[n][k] = *(const LAS bf16x8*)(lds + PG8_SB(b, h) + boff + n * 2048 + k * 1024); } while (0)
; #define PG8_MMA(ai, bj, At, Bt) do { __builtin_amdgcn_s_setprio(1); _Pragma("unroll") for (int m = 0; m < 4; ++m) _Pragma("unroll") for (int n = 0; n < 2; ++n) _Pragma("unroll") for (int k = 0; k < 2; ++k) \
;         acc[ai][bj][m][n] = __builtin_amdgcn_mfma_f32_16x16x32_bf16(Bt[n][k], At[m][k], acc[ai][bj][m][n], 0, 0, 0); __builtin_amdgcn_s_setprio(0); } while (0)
; #define PG8_WAIT_V(n) asm volatile("s_waitcnt vmcnt(" #n ")" ::: "memory")
; #define PG8_WAIT_L(n) asm volatile("s_waitcnt lgkmcnt(" #n ")" ::: "memory")
; #define PG8_BAR __builtin_amdgcn_s_barrier()
; #define PG8_SCHED __builtin_amdgcn_sched_barrier(0)
; template <class Epi>
; __device__ __forceinline__ void gemm_phase(LAS unsigned char* lds, const Gemm g, const StaticOrder& S, const Epi& E) {
;     ...
;         for (int t = 0; t < nt; t += 2) {
;             const bool last = (t == nt - 2);
;             const char* a1 = cA + (size_t)(t + 1) * kstep;
;             const char* a2 = last ? nA : cA + (size_t)(t + 2) * kstep; const char* b2 = last ? nB : cB + (size_t)(t + 2) * kstep;
;             const char* a3 = a2 + kstep; const char* b3 = b2 + kstep;
;             PG8_LDB(B0, 0, 0); PG8_LDB(B1, 0, 1); PG8_SCHED; PG8_LDA(At, 0, 0); PG8_STAGE(PG8_SA(1, 1), a1 + hstep, voffA);
;             PG8_WAIT_V(8); PG8_WAIT_L(0); PG8_BAR; PG8_MMA(0, 0, At, B0); PG8_MMA(0, 1, At, B1); PG8_BAR; PG8_SCHED;
;             PG8_LDA(At, 0, 1); PG8_STAGE(PG8_SB(0, 0), b2, voffB); PG8_STAGE(PG8_SB(0, 1), b2 + hstep, voffB); PG8_STAGE(PG8_SA(0, 0), a2, voffA);
.LBB0_221:
	s_add_u32 s0, s6, 0x80
	s_addc_u32 s1, s7, 0
	s_add_u32 s6, s4, 0x100
	s_addc_u32 s7, s5, 0
	s_mov_b32 s4, 0
	s_waitcnt vmcnt(0)
	s_and_b64 vcc, exec, s[44:45]
	s_cbranch_vccz .Lk_grpb
	s_add_i32 s71, s4, 2
	s_add_u32 s72, s0, 0x80
	s_addc_u32 s5, s1, 0
	s_add_i32 s74, 0, 0x10000
	s_cmp_eq_u32 s62, s4
	s_cselect_b32 s5, s49, s5
	s_cselect_b32 s4, s48, s72
	s_cselect_b32 s73, s51, s7
	s_cselect_b32 s72, s50, s6
	s_add_i32 s75, 0, 0x14000
	v_add_u32_e32 v140, s74, v245
	v_add_u32_e32 v156, s75, v245
	ds_read_b128 v[128:131], v140
	ds_read_b128 v[132:135], v140 offset:1024
	ds_read_b128 v[136:139], v140 offset:2048
	ds_read_b128 v[140:143], v140 offset:3072
	ds_read_b128 v[144:147], v156
	ds_read_b128 v[148:151], v156 offset:1024
	ds_read_b128 v[152:155], v156 offset:2048
	ds_read_b128 v[156:159], v156 offset:3072
	v_lshl_add_u64 v[212:213], s[0:1], 0, v[208:209]
	s_add_i32 m0, s55, 0xc000
	ds_read_b128 v[160:163], v247
	ds_read_b128 v[164:167], v247 offset:1024
	ds_read_b128 v[168:171], v247 offset:2048
	ds_read_b128 v[172:175], v247 offset:3072
	ds_read_b128 v[176:179], v247 offset:4096
	ds_read_b128 v[180:183], v247 offset:5120
	ds_read_b128 v[184:187], v247 offset:6144
	ds_read_b128 v[188:191], v247 offset:7168
	global_load_lds_dwordx4 v[212:213], off
	v_lshl_add_u64 v[212:213], s[0:1], 0, v[210:211]
	s_add_i32 m0, s55, 0xe000
	s_nop 0
	global_load_lds_dwordx4 v[212:213], off
	s_waitcnt lgkmcnt(0)
	s_barrier
	s_setprio 1
	s_waitcnt lgkmcnt(0)
	v_mfma_f32_16x16x32_bf16 v[124:127], v[128:131], v[160:163], 0
	v_mfma_f32_16x16x32_bf16 v[120:123], v[136:139], v[160:163], 0
	v_mfma_f32_16x16x32_bf16 v[108:111], v[128:131], v[168:171], 0
	v_mfma_f32_16x16x32_bf16 v[104:107], v[136:139], v[168:171], 0
	v_mfma_f32_16x16x32_bf16 v[92:95], v[128:131], v[176:179], 0
	v_mfma_f32_16x16x32_bf16 v[88:91], v[136:139], v[176:179], 0
	v_mfma_f32_16x16x32_bf16 v[76:79], v[128:131], v[184:187], 0
	v_mfma_f32_16x16x32_bf16 v[72:75], v[136:139], v[184:187], 0
	v_mfma_f32_16x16x32_bf16 v[124:127], v[132:135], v[164:167], v[124:127]
	v_mfma_f32_16x16x32_bf16 v[120:123], v[140:143], v[164:167], v[120:123]
	v_mfma_f32_16x16x32_bf16 v[108:111], v[132:135], v[172:175], v[108:111]
	v_mfma_f32_16x16x32_bf16 v[104:107], v[140:143], v[172:175], v[104:107]
	v_mfma_f32_16x16x32_bf16 v[92:95], v[132:135], v[180:183], v[92:95]
	v_mfma_f32_16x16x32_bf16 v[88:91], v[140:143], v[180:183], v[88:91]
	v_mfma_f32_16x16x32_bf16 v[76:79], v[132:135], v[188:191], v[76:79]
	v_mfma_f32_16x16x32_bf16 v[72:75], v[140:143], v[188:191], v[72:75]
	s_setprio 0
	s_setprio 1
	v_mfma_f32_16x16x32_bf16 v[116:119], v[144:147], v[160:163], 0
	v_mfma_f32_16x16x32_bf16 v[112:115], v[152:155], v[160:163], 0
	v_mfma_f32_16x16x32_bf16 v[100:103], v[144:147], v[168:171], 0
	v_mfma_f32_16x16x32_bf16 v[96:99], v[152:155], v[168:171], 0
	v_mfma_f32_16x16x32_bf16 v[84:87], v[144:147], v[176:179], 0
	v_mfma_f32_16x16x32_bf16 v[80:83], v[152:155], v[176:179], 0
	v_mfma_f32_16x16x32_bf16 v[68:71], v[144:147], v[184:187], 0
	v_mfma_f32_16x16x32_bf16 v[64:67], v[152:155], v[184:187], 0
	v_mfma_f32_16x16x32_bf16 v[116:119], v[148:151], v[164:167], v[116:119]
	v_mfma_f32_16x16x32_bf16 v[112:115], v[156:159], v[164:167], v[112:115]
	v_mfma_f32_16x16x32_bf16 v[100:103], v[148:151], v[172:175], v[100:103]
	v_mfma_f32_16x16x32_bf16 v[96:99], v[156:159], v[172:175], v[96:99]
	v_mfma_f32_16x16x32_bf16 v[84:87], v[148:151], v[180:183], v[84:87]
	v_mfma_f32_16x16x32_bf16 v[80:83], v[156:159], v[180:183], v[80:83]
	v_mfma_f32_16x16x32_bf16 v[68:71], v[148:151], v[188:191], v[68:71]
	v_mfma_f32_16x16x32_bf16 v[64:67], v[156:159], v[188:191], v[64:67]
	s_setprio 0
	s_waitcnt vmcnt(8)
	s_barrier
	s_add_i32 s74, s74, s54
	v_lshl_add_u64 v[212:213], s[72:73], 0, v[192:193]
	s_mov_b32 m0, s74
	ds_read_b128 v[160:163], v247 offset:16384
	ds_read_b128 v[164:167], v247 offset:17408
	ds_read_b128 v[168:171], v247 offset:18432
	ds_read_b128 v[172:175], v247 offset:19456
	ds_read_b128 v[176:179], v247 offset:20480
	ds_read_b128 v[180:183], v247 offset:21504
	ds_read_b128 v[184:187], v247 offset:22528
	ds_read_b128 v[188:191], v247 offset:23552
	global_load_lds_dwordx4 v[212:213], off
	s_add_i32 m0, s74, 0x2000
	v_lshl_add_u64 v[214:215], s[72:73], 0, v[204:205]
	s_add_u32 s72, s72, s2
	s_addc_u32 s73, s73, 0
	s_add_i32 s74, s75, s54
	global_load_lds_dwordx4 v[214:215], off
	v_lshl_add_u64 v[216:217], s[72:73], 0, v[192:193]
	s_mov_b32 m0, s74
	v_lshl_add_u64 v[218:219], s[72:73], 0, v[204:205]
	global_load_lds_dwordx4 v[216:217], off
	s_add_i32 m0, s74, 0x2000
	v_lshl_add_u64 v[220:221], s[4:5], 0, v[200:201]
	global_load_lds_dwordx4 v[218:219], off
	s_mov_b32 m0, s55
	v_lshl_add_u64 v[222:223], s[4:5], 0, v[202:203]
	global_load_lds_dwordx4 v[220:221], off
	s_mov_b32 m0, s56
	s_nop 0
	global_load_lds_dwordx4 v[222:223], off
	s_waitcnt lgkmcnt(0)
	s_barrier
; #define PG8_STAGE(bufoff, gbase, voff) do { _Pragma("unroll") for (int _i = 0; _i < 2; ++_i) \
;         __builtin_amdgcn_global_load_lds((const unsigned*)((const char*)(gbase) + (voff)[_i]), (LAS unsigned*)(lds + (bufoff) + ldsw + _i * 8192), 16, 0, 0); } while (0)
; #define PG8_LDA(dst, b, h) do { _Pragma("unroll") for (int m = 0; m < 4; ++m) _Pragma("unroll") for (int k = 0; k < 2; ++k) dst[m][k] = *(const LAS bf16x8*)(lds + PG8_SA(b, h) + aoff + m * 2048 + k * 1024); } while (0)
; #define PG8_LDB(dst, b, h) do { _Pragma("unroll") for (int n = 0; n < 2; ++n) _Pragma("unroll") for (int k = 0; k < 2; ++k) dst[n][k] = *(const LAS bf16x8*)(lds + PG8_SB(b, h) + boff + n * 2048 + k * 1024); } while (0)
; #define PG8_MMA(ai, bj, At, Bt) do { __builtin_amdgcn_s_setprio(1); _Pragma("unroll") for (int m = 0; m < 4; ++m) _Pragma("unroll") for (int n = 0; n < 2; ++n) _Pragma("unroll") for (int k = 0; k < 2; ++k) \
;         acc[ai][bj][m][n] = __builtin_amdgcn_mfma_f32_16x16x32_bf16(Bt[n][k], At[m][k], acc[ai][bj][m][n], 0, 0, 0); __builtin_amdgcn_s_setprio(0); } while (0)
; #define PG8_WAIT_V(n) asm volatile("s_waitcnt vmcnt(" #n ")" ::: "memory")
; #define PG8_WAIT_L(n) asm volatile("s_waitcnt lgkmcnt(" #n ")" ::: "memory")
; #define PG8_BAR __builtin_amdgcn_s_barrier()
; #define PG8_SCHED __builtin_amdgcn_sched_barrier(0)
; template <class Epi>
; __device__ __forceinline__ void gemm_phase(LAS unsigned char* lds, const Gemm g, const StaticOrder& S, const Epi& E) {
;     ...
;             PG8_LDA(At, 0, 1); PG8_STAGE(PG8_SB(0, 0), b2, voffB); PG8_STAGE(PG8_SB(0, 1), b2 + hstep, voffB); PG8_STAGE(PG8_SA(0, 0), a2, voffA);
;             PG8_WAIT_V(8); PG8_WAIT_L(0); PG8_BAR; PG8_MMA(1, 0, At, B0); PG8_MMA(1, 1, At, B1); PG8_BAR; PG8_SCHED;
;             PG8_LDB(B0, 1, 0); PG8_LDB(B1, 1, 1); PG8_SCHED; PG8_LDA(At, 1, 0); PG8_STAGE(PG8_SA(0, 1), a2 + hstep, voffA);
;             PG8_WAIT_V(8); PG8_WAIT_L(0); PG8_BAR; PG8_MMA(0, 0, At, B0); PG8_MMA(0, 1, At, B1); PG8_BAR; PG8_SCHED;
;             PG8_LDA(At, 1, 1); PG8_STAGE(PG8_SB(1, 0), b3, voffB); PG8_STAGE(PG8_SB(1, 1), b3 + hstep, voffB); PG8_STAGE(PG8_SA(1, 0), a3, voffA);
	s_setprio 1
	s_waitcnt lgkmcnt(0)
	v_mfma_f32_16x16x32_bf16 v[60:63], v[128:131], v[160:163], 0
	v_mfma_f32_16x16x32_bf16 v[56:59], v[136:139], v[160:163], 0
	v_mfma_f32_16x16x32_bf16 v[44:47], v[128:131], v[168:171], 0
	v_mfma_f32_16x16x32_bf16 v[40:43], v[136:139], v[168:171], 0
	v_mfma_f32_16x16x32_bf16 v[28:31], v[128:131], v[176:179], 0
	v_mfma_f32_16x16x32_bf16 v[24:27], v[136:139], v[176:179], 0
	v_mfma_f32_16x16x32_bf16 v[12:15], v[128:131], v[184:187], 0
	v_mfma_f32_16x16x32_bf16 v[8:11], v[136:139], v[184:187], 0
	v_mfma_f32_16x16x32_bf16 v[60:63], v[132:135], v[164:167], v[60:63]
	v_mfma_f32_16x16x32_bf16 v[56:59], v[140:143], v[164:167], v[56:59]
	v_mfma_f32_16x16x32_bf16 v[44:47], v[132:135], v[172:175], v[44:47]
	v_mfma_f32_16x16x32_bf16 v[40:43], v[140:143], v[172:175], v[40:43]
	v_mfma_f32_16x16x32_bf16 v[28:31], v[132:135], v[180:183], v[28:31]
	v_mfma_f32_16x16x32_bf16 v[24:27], v[140:143], v[180:183], v[24:27]
	v_mfma_f32_16x16x32_bf16 v[12:15], v[132:135], v[188:191], v[12:15]
	v_mfma_f32_16x16x32_bf16 v[8:11], v[140:143], v[188:191], v[8:11]
	s_setprio 0
	s_setprio 1
	v_mfma_f32_16x16x32_bf16 v[52:55], v[144:147], v[160:163], 0
	v_mfma_f32_16x16x32_bf16 v[48:51], v[152:155], v[160:163], 0
	v_mfma_f32_16x16x32_bf16 v[36:39], v[144:147], v[168:171], 0
	v_mfma_f32_16x16x32_bf16 v[32:35], v[152:155], v[168:171], 0
	v_mfma_f32_16x16x32_bf16 v[20:23], v[144:147], v[176:179], 0
	v_mfma_f32_16x16x32_bf16 v[16:19], v[152:155], v[176:179], 0
	v_mfma_f32_16x16x32_bf16 v[4:7], v[144:147], v[184:187], 0
	v_mfma_f32_16x16x32_bf16 v[0:3], v[152:155], v[184:187], 0
	v_mfma_f32_16x16x32_bf16 v[52:55], v[148:151], v[164:167], v[52:55]
	v_mfma_f32_16x16x32_bf16 v[48:51], v[156:159], v[164:167], v[48:51]
	v_mfma_f32_16x16x32_bf16 v[36:39], v[148:151], v[172:175], v[36:39]
	v_mfma_f32_16x16x32_bf16 v[32:35], v[156:159], v[172:175], v[32:35]
	v_mfma_f32_16x16x32_bf16 v[20:23], v[148:151], v[180:183], v[20:23]
	v_mfma_f32_16x16x32_bf16 v[16:19], v[156:159], v[180:183], v[16:19]
	v_mfma_f32_16x16x32_bf16 v[4:7], v[148:151], v[188:191], v[4:7]
	v_mfma_f32_16x16x32_bf16 v[0:3], v[156:159], v[188:191], v[0:3]
	s_setprio 0
	s_waitcnt vmcnt(8)
	s_barrier
	s_add_i32 s72, 0, 0x18000
	s_add_i32 s73, 0, 0x1c000
	v_add_u32_e32 v140, s72, v245
	v_add_u32_e32 v156, s73, v245
	ds_read_b128 v[128:131], v140
	ds_read_b128 v[132:135], v140 offset:1024
	ds_read_b128 v[136:139], v140 offset:2048
	ds_read_b128 v[140:143], v140 offset:3072
	ds_read_b128 v[144:147], v156
	ds_read_b128 v[148:151], v156 offset:1024
	ds_read_b128 v[152:155], v156 offset:2048
	ds_read_b128 v[156:159], v156 offset:3072
	s_add_u32 s4, s4, s2
	s_addc_u32 s5, s5, 0
	s_mov_b32 m0, s57
	v_lshl_add_u64 v[224:225], s[4:5], 0, v[200:201]
	ds_read_b128 v[160:163], v247 offset:32768
	ds_read_b128 v[164:167], v247 offset:33792
	ds_read_b128 v[168:171], v247 offset:34816
	ds_read_b128 v[172:175], v247 offset:35840
	ds_read_b128 v[176:179], v247 offset:36864
	ds_read_b128 v[180:183], v247 offset:37888
	ds_read_b128 v[184:187], v247 offset:38912
	ds_read_b128 v[188:191], v247 offset:39936
	global_load_lds_dwordx4 v[224:225], off
	v_lshl_add_u64 v[224:225], s[4:5], 0, v[202:203]
	s_mov_b32 m0, s58
	s_nop 0
	global_load_lds_dwordx4 v[224:225], off
	s_waitcnt lgkmcnt(0)
	s_barrier
	s_setprio 1
	s_waitcnt lgkmcnt(0)
	v_mfma_f32_16x16x32_bf16 v[124:127], v[128:131], v[160:163], v[124:127]
	v_mfma_f32_16x16x32_bf16 v[120:123], v[136:139], v[160:163], v[120:123]
	v_mfma_f32_16x16x32_bf16 v[108:111], v[128:131], v[168:171], v[108:111]
	v_mfma_f32_16x16x32_bf16 v[104:107], v[136:139], v[168:171], v[104:107]
	v_mfma_f32_16x16x32_bf16 v[92:95], v[128:131], v[176:179], v[92:95]
	v_mfma_f32_16x16x32_bf16 v[88:91], v[136:139], v[176:179], v[88:91]
	v_mfma_f32_16x16x32_bf16 v[76:79], v[128:131], v[184:187], v[76:79]
	v_mfma_f32_16x16x32_bf16 v[72:75], v[136:139], v[184:187], v[72:75]
	v_mfma_f32_16x16x32_bf16 v[124:127], v[132:135], v[164:167], v[124:127]
	v_mfma_f32_16x16x32_bf16 v[120:123], v[140:143], v[164:167], v[120:123]
	v_mfma_f32_16x16x32_bf16 v[108:111], v[132:135], v[172:175], v[108:111]
	v_mfma_f32_16x16x32_bf16 v[104:107], v[140:143], v[172:175], v[104:107]
	v_mfma_f32_16x16x32_bf16 v[92:95], v[132:135], v[180:183], v[92:95]
	v_mfma_f32_16x16x32_bf16 v[88:91], v[140:143], v[180:183], v[88:91]
	v_mfma_f32_16x16x32_bf16 v[76:79], v[132:135], v[188:191], v[76:79]
	v_mfma_f32_16x16x32_bf16 v[72:75], v[140:143], v[188:191], v[72:75]
	s_setprio 0
	s_setprio 1
	v_mfma_f32_16x16x32_bf16 v[116:119], v[144:147], v[160:163], v[116:119]
	v_mfma_f32_16x16x32_bf16 v[112:115], v[152:155], v[160:163], v[112:115]
	v_mfma_f32_16x16x32_bf16 v[100:103], v[144:147], v[168:171], v[100:103]
	v_mfma_f32_16x16x32_bf16 v[96:99], v[152:155], v[168:171], v[96:99]
	v_mfma_f32_16x16x32_bf16 v[84:87], v[144:147], v[176:179], v[84:87]
	v_mfma_f32_16x16x32_bf16 v[80:83], v[152:155], v[176:179], v[80:83]
	v_mfma_f32_16x16x32_bf16 v[68:71], v[144:147], v[184:187], v[68:71]
	v_mfma_f32_16x16x32_bf16 v[64:67], v[152:155], v[184:187], v[64:67]
	v_mfma_f32_16x16x32_bf16 v[116:119], v[148:151], v[164:167], v[116:119]
	v_mfma_f32_16x16x32_bf16 v[112:115], v[156:159], v[164:167], v[112:115]
	v_mfma_f32_16x16x32_bf16 v[100:103], v[148:151], v[172:175], v[100:103]
	v_mfma_f32_16x16x32_bf16 v[96:99], v[156:159], v[172:175], v[96:99]
	v_mfma_f32_16x16x32_bf16 v[84:87], v[148:151], v[180:183], v[84:87]
	v_mfma_f32_16x16x32_bf16 v[80:83], v[156:159], v[180:183], v[80:83]
	v_mfma_f32_16x16x32_bf16 v[68:71], v[148:151], v[188:191], v[68:71]
	v_mfma_f32_16x16x32_bf16 v[64:67], v[156:159], v[188:191], v[64:67]
	s_setprio 0
	s_waitcnt vmcnt(8)
	s_barrier
; #define PG8_STAGE(bufoff, gbase, voff) do { _Pragma("unroll") for (int _i = 0; _i < 2; ++_i) \
;         __builtin_amdgcn_global_load_lds((const unsigned*)((const char*)(gbase) + (voff)[_i]), (LAS unsigned*)(lds + (bufoff) + ldsw + _i * 8192), 16, 0, 0); } while (0)
; #define PG8_LDA(dst, b, h) do { _Pragma("unroll") for (int m = 0; m < 4; ++m) _Pragma("unroll") for (int k = 0; k < 2; ++k) dst[m][k] = *(const LAS bf16x8*)(lds + PG8_SA(b, h) + aoff + m * 2048 + k * 1024); } while (0)
; #define PG8_LDB(dst, b, h) do { _Pragma("unroll") for (int n = 0; n < 2; ++n) _Pragma("unroll") for (int k = 0; k < 2; ++k) dst[n][k] = *(const LAS bf16x8*)(lds + PG8_SB(b, h) + boff + n * 2048 + k * 1024); } while (0)
; #define PG8_MMA(ai, bj, At, Bt) do { __builtin_amdgcn_s_setprio(1); _Pragma("unroll") for (int m = 0; m < 4; ++m) _Pragma("unroll") for (int n = 0; n < 2; ++n) _Pragma("unroll") for (int k = 0; k < 2; ++k) \
;         acc[ai][bj][m][n] = __builtin_amdgcn_mfma_f32_16x16x32_bf16(Bt[n][k], At[m][k], acc[ai][bj][m][n], 0, 0, 0); __builtin_amdgcn_s_setprio(0); } while (0)
; #define PG8_WAIT_V(n) asm volatile("s_waitcnt vmcnt(" #n ")" ::: "memory")
; #define PG8_WAIT_L(n) asm volatile("s_waitcnt lgkmcnt(" #n ")" ::: "memory")
; #define PG8_BAR __builtin_amdgcn_s_barrier()
; #define PG8_SCHED __builtin_amdgcn_sched_barrier(0)
; template <class Epi>
; __device__ __forceinline__ void gemm_phase(LAS unsigned char* lds, const Gemm g, const StaticOrder& S, const Epi& E) {
;     ...
;         for (int t = 0; t < nt; t += 2) {
;             const bool last = (t == nt - 2);
;             const char* a1 = cA + (size_t)(t + 1) * kstep;
;             const char* a2 = last ? nA : cA + (size_t)(t + 2) * kstep; const char* b2 = last ? nB : cB + (size_t)(t + 2) * kstep;
;             const char* a3 = a2 + kstep; const char* b3 = b2 + kstep;
;             PG8_LDB(B0, 0, 0); PG8_LDB(B1, 0, 1); PG8_SCHED; PG8_LDA(At, 0, 0); PG8_STAGE(PG8_SA(1, 1), a1 + hstep, voffA);
;     ...
;             PG8_LDA(At, 1, 1); PG8_STAGE(PG8_SB(1, 0), b3, voffB); PG8_STAGE(PG8_SB(1, 1), b3 + hstep, voffB); PG8_STAGE(PG8_SA(1, 0), a3, voffA);
;             PG8_WAIT_V(8); PG8_WAIT_L(0); PG8_BAR; PG8_MMA(1, 0, At, B0); PG8_MMA(1, 1, At, B1); PG8_BAR; PG8_SCHED;
	s_add_i32 s4, s72, s54
	v_lshl_add_u64 v[212:213], v[212:213], 0, s[12:13]
	s_mov_b32 m0, s4
	ds_read_b128 v[160:163], v247 offset:49152
	ds_read_b128 v[164:167], v247 offset:50176
	ds_read_b128 v[168:171], v247 offset:51200
	ds_read_b128 v[172:175], v247 offset:52224
	ds_read_b128 v[176:179], v247 offset:53248
	ds_read_b128 v[180:183], v247 offset:54272
	ds_read_b128 v[184:187], v247 offset:55296
	ds_read_b128 v[188:191], v247 offset:56320
	global_load_lds_dwordx4 v[212:213], off
	v_lshl_add_u64 v[212:213], v[214:215], 0, s[12:13]
	s_add_i32 m0, s4, 0x2000
	s_add_i32 s4, s73, s54
	global_load_lds_dwordx4 v[212:213], off
	v_lshl_add_u64 v[212:213], v[216:217], 0, s[12:13]
	s_mov_b32 m0, s4
	s_nop 0
	global_load_lds_dwordx4 v[212:213], off
	v_lshl_add_u64 v[212:213], v[218:219], 0, s[12:13]
	s_add_i32 m0, s4, 0x2000
	s_nop 0
	global_load_lds_dwordx4 v[212:213], off
	v_lshl_add_u64 v[212:213], v[220:221], 0, s[12:13]
	s_mov_b32 m0, s59
	s_nop 0
	global_load_lds_dwordx4 v[212:213], off
	v_lshl_add_u64 v[212:213], v[222:223], 0, s[12:13]
	s_mov_b32 m0, s60
	s_nop 0
	global_load_lds_dwordx4 v[212:213], off
	s_waitcnt lgkmcnt(0)
	s_barrier
	s_setprio 1
	s_waitcnt lgkmcnt(0)
	v_mfma_f32_16x16x32_bf16 v[60:63], v[128:131], v[160:163], v[60:63]
	v_mfma_f32_16x16x32_bf16 v[56:59], v[136:139], v[160:163], v[56:59]
	v_mfma_f32_16x16x32_bf16 v[44:47], v[128:131], v[168:171], v[44:47]
	v_mfma_f32_16x16x32_bf16 v[40:43], v[136:139], v[168:171], v[40:43]
	v_mfma_f32_16x16x32_bf16 v[28:31], v[128:131], v[176:179], v[28:31]
	v_mfma_f32_16x16x32_bf16 v[24:27], v[136:139], v[176:179], v[24:27]
	v_mfma_f32_16x16x32_bf16 v[12:15], v[128:131], v[184:187], v[12:15]
	v_mfma_f32_16x16x32_bf16 v[8:11], v[136:139], v[184:187], v[8:11]
	v_mfma_f32_16x16x32_bf16 v[60:63], v[132:135], v[164:167], v[60:63]
	v_mfma_f32_16x16x32_bf16 v[56:59], v[140:143], v[164:167], v[56:59]
	v_mfma_f32_16x16x32_bf16 v[44:47], v[132:135], v[172:175], v[44:47]
	v_mfma_f32_16x16x32_bf16 v[40:43], v[140:143], v[172:175], v[40:43]
	v_mfma_f32_16x16x32_bf16 v[28:31], v[132:135], v[180:183], v[28:31]
	v_mfma_f32_16x16x32_bf16 v[24:27], v[140:143], v[180:183], v[24:27]
	v_mfma_f32_16x16x32_bf16 v[12:15], v[132:135], v[188:191], v[12:15]
	v_mfma_f32_16x16x32_bf16 v[8:11], v[140:143], v[188:191], v[8:11]
	s_setprio 0
	s_setprio 1
	v_mfma_f32_16x16x32_bf16 v[52:55], v[144:147], v[160:163], v[52:55]
	v_mfma_f32_16x16x32_bf16 v[48:51], v[152:155], v[160:163], v[48:51]
	v_mfma_f32_16x16x32_bf16 v[36:39], v[144:147], v[168:171], v[36:39]
	v_mfma_f32_16x16x32_bf16 v[32:35], v[152:155], v[168:171], v[32:35]
	v_mfma_f32_16x16x32_bf16 v[20:23], v[144:147], v[176:179], v[20:23]
	v_mfma_f32_16x16x32_bf16 v[16:19], v[152:155], v[176:179], v[16:19]
	v_mfma_f32_16x16x32_bf16 v[4:7], v[144:147], v[184:187], v[4:7]
	v_mfma_f32_16x16x32_bf16 v[0:3], v[152:155], v[184:187], v[0:3]
	v_mfma_f32_16x16x32_bf16 v[52:55], v[148:151], v[164:167], v[52:55]
	v_mfma_f32_16x16x32_bf16 v[48:51], v[156:159], v[164:167], v[48:51]
	v_mfma_f32_16x16x32_bf16 v[36:39], v[148:151], v[172:175], v[36:39]
	v_mfma_f32_16x16x32_bf16 v[32:35], v[156:159], v[172:175], v[32:35]
	v_mfma_f32_16x16x32_bf16 v[20:23], v[148:151], v[180:183], v[20:23]
	v_mfma_f32_16x16x32_bf16 v[16:19], v[156:159], v[180:183], v[16:19]
	v_mfma_f32_16x16x32_bf16 v[4:7], v[148:151], v[188:191], v[4:7]
	v_mfma_f32_16x16x32_bf16 v[0:3], v[156:159], v[188:191], v[0:3]
	s_setprio 0
	s_waitcnt vmcnt(8)
	s_barrier
	s_add_u32 s0, s0, 0x100
	s_addc_u32 s1, s1, 0
	s_add_u32 s6, s6, 0x100
	s_addc_u32 s7, s7, 0
	s_cmp_ge_u32 s71, s61
	s_mov_b32 s4, s71
	s_cbranch_scc1 .Lk_done
.Lk_ra:
	s_add_i32 s71, s4, 2
	s_add_u32 s72, s0, 0x80
	s_addc_u32 s5, s1, 0
	s_add_i32 s74, 0, 0x10000
	s_cmp_eq_u32 s62, s4
	s_cselect_b32 s5, s49, s5
	s_cselect_b32 s4, s48, s72
	s_cselect_b32 s73, s51, s7
	s_cselect_b32 s72, s50, s6
	s_add_i32 s75, 0, 0x14000
	v_add_u32_e32 v140, s74, v245
	v_add_u32_e32 v156, s75, v245
	ds_read_b128 v[128:131], v140
	ds_read_b128 v[132:135], v140 offset:1024
	ds_read_b128 v[136:139], v140 offset:2048
	ds_read_b128 v[140:143], v140 offset:3072
	ds_read_b128 v[144:147], v156
	ds_read_b128 v[148:151], v156 offset:1024
	ds_read_b128 v[152:155], v156 offset:2048
	ds_read_b128 v[156:159], v156 offset:3072
	v_lshl_add_u64 v[212:213], s[0:1], 0, v[208:209]
	s_add_i32 m0, s55, 0xc000
	ds_read_b128 v[160:163], v247
	ds_read_b128 v[164:167], v247 offset:1024
	ds_read_b128 v[168:171], v247 offset:2048
	ds_read_b128 v[172:175], v247 offset:3072
	ds_read_b128 v[176:179], v247 offset:4096
	ds_read_b128 v[180:183], v247 offset:5120
	ds_read_b128 v[184:187], v247 offset:6144
	ds_read_b128 v[188:191], v247 offset:7168
	global_load_lds_dwordx4 v[212:213], off
	v_lshl_add_u64 v[212:213], s[0:1], 0, v[210:211]
	s_add_i32 m0, s55, 0xe000
	s_nop 0
	global_load_lds_dwordx4 v[212:213], off
	s_waitcnt lgkmcnt(0)
	s_barrier
; #define PG8_STAGE(bufoff, gbase, voff) do { _Pragma("unroll") for (int _i = 0; _i < 2; ++_i) \
;         __builtin_amdgcn_global_load_lds((const unsigned*)((const char*)(gbase) + (voff)[_i]), (LAS unsigned*)(lds + (bufoff) + ldsw + _i * 8192), 16, 0, 0); } while (0)
; #define PG8_LDA(dst, b, h) do { _Pragma("unroll") for (int m = 0; m < 4; ++m) _Pragma("unroll") for (int k = 0; k < 2; ++k) dst[m][k] = *(const LAS bf16x8*)(lds + PG8_SA(b, h) + aoff + m * 2048 + k * 1024); } while (0)
; #define PG8_MMA(ai, bj, At, Bt) do { __builtin_amdgcn_s_setprio(1); _Pragma("unroll") for (int m = 0; m < 4; ++m) _Pragma("unroll") for (int n = 0; n < 2; ++n) _Pragma("unroll") for (int k = 0; k < 2; ++k) \
;         acc[ai][bj][m][n] = __builtin_amdgcn_mfma_f32_16x16x32_bf16(Bt[n][k], At[m][k], acc[ai][bj][m][n], 0, 0, 0); __builtin_amdgcn_s_setprio(0); } while (0)
; #define PG8_WAIT_V(n) asm volatile("s_waitcnt vmcnt(" #n ")" ::: "memory")
; #define PG8_WAIT_L(n) asm volatile("s_waitcnt lgkmcnt(" #n ")" ::: "memory")
; #define PG8_BAR __builtin_amdgcn_s_barrier()
; #define PG8_SCHED __builtin_amdgcn_sched_barrier(0)
; template <class Epi>
; __device__ __forceinline__ void gemm_phase(LAS unsigned char* lds, const Gemm g, const StaticOrder& S, const Epi& E) {
;     ...
;             PG8_WAIT_V(8); PG8_WAIT_L(0); PG8_BAR; PG8_MMA(0, 0, At, B0); PG8_MMA(0, 1, At, B1); PG8_BAR; PG8_SCHED;
;             PG8_LDA(At, 0, 1); PG8_STAGE(PG8_SB(0, 0), b2, voffB); PG8_STAGE(PG8_SB(0, 1), b2 + hstep, voffB); PG8_STAGE(PG8_SA(0, 0), a2, voffA);
;             PG8_WAIT_V(8); PG8_WAIT_L(0); PG8_BAR; PG8_MMA(1, 0, At, B0); PG8_MMA(1, 1, At, B1); PG8_BAR; PG8_SCHED;
	s_setprio 1
	s_waitcnt lgkmcnt(0)
	v_mfma_f32_16x16x32_bf16 v[124:127], v[128:131], v[160:163], v[124:127]
	v_mfma_f32_16x16x32_bf16 v[120:123], v[136:139], v[160:163], v[120:123]
	v_mfma_f32_16x16x32_bf16 v[108:111], v[128:131], v[168:171], v[108:111]
	v_mfma_f32_16x16x32_bf16 v[104:107], v[136:139], v[168:171], v[104:107]
	v_mfma_f32_16x16x32_bf16 v[92:95], v[128:131], v[176:179], v[92:95]
	v_mfma_f32_16x16x32_bf16 v[88:91], v[136:139], v[176:179], v[88:91]
	v_mfma_f32_16x16x32_bf16 v[76:79], v[128:131], v[184:187], v[76:79]
	v_mfma_f32_16x16x32_bf16 v[72:75], v[136:139], v[184:187], v[72:75]
	v_mfma_f32_16x16x32_bf16 v[124:127], v[132:135], v[164:167], v[124:127]
	v_mfma_f32_16x16x32_bf16 v[120:123], v[140:143], v[164:167], v[120:123]
	v_mfma_f32_16x16x32_bf16 v[108:111], v[132:135], v[172:175], v[108:111]
	v_mfma_f32_16x16x32_bf16 v[104:107], v[140:143], v[172:175], v[104:107]
	v_mfma_f32_16x16x32_bf16 v[92:95], v[132:135], v[180:183], v[92:95]
	v_mfma_f32_16x16x32_bf16 v[88:91], v[140:143], v[180:183], v[88:91]
	v_mfma_f32_16x16x32_bf16 v[76:79], v[132:135], v[188:191], v[76:79]
	v_mfma_f32_16x16x32_bf16 v[72:75], v[140:143], v[188:191], v[72:75]
	s_setprio 0
	s_setprio 1
	v_mfma_f32_16x16x32_bf16 v[116:119], v[144:147], v[160:163], v[116:119]
	v_mfma_f32_16x16x32_bf16 v[112:115], v[152:155], v[160:163], v[112:115]
	v_mfma_f32_16x16x32_bf16 v[100:103], v[144:147], v[168:171], v[100:103]
	v_mfma_f32_16x16x32_bf16 v[96:99], v[152:155], v[168:171], v[96:99]
	v_mfma_f32_16x16x32_bf16 v[84:87], v[144:147], v[176:179], v[84:87]
	v_mfma_f32_16x16x32_bf16 v[80:83], v[152:155], v[176:179], v[80:83]
	v_mfma_f32_16x16x32_bf16 v[68:71], v[144:147], v[184:187], v[68:71]
	v_mfma_f32_16x16x32_bf16 v[64:67], v[152:155], v[184:187], v[64:67]
	v_mfma_f32_16x16x32_bf16 v[116:119], v[148:151], v[164:167], v[116:119]
	v_mfma_f32_16x16x32_bf16 v[112:115], v[156:159], v[164:167], v[112:115]
	v_mfma_f32_16x16x32_bf16 v[100:103], v[148:151], v[172:175], v[100:103]
	v_mfma_f32_16x16x32_bf16 v[96:99], v[156:159], v[172:175], v[96:99]
	v_mfma_f32_16x16x32_bf16 v[84:87], v[148:151], v[180:183], v[84:87]
	v_mfma_f32_16x16x32_bf16 v[80:83], v[156:159], v[180:183], v[80:83]
	v_mfma_f32_16x16x32_bf16 v[68:71], v[148:151], v[188:191], v[68:71]
	v_mfma_f32_16x16x32_bf16 v[64:67], v[156:159], v[188:191], v[64:67]
	s_setprio 0
	s_waitcnt vmcnt(8)
	s_barrier
	s_add_i32 s74, s74, s54
	v_lshl_add_u64 v[212:213], s[72:73], 0, v[192:193]
	s_mov_b32 m0, s74
	ds_read_b128 v[160:163], v247 offset:16384
	ds_read_b128 v[164:167], v247 offset:17408
	ds_read_b128 v[168:171], v247 offset:18432
	ds_read_b128 v[172:175], v247 offset:19456
	ds_read_b128 v[176:179], v247 offset:20480
	ds_read_b128 v[180:183], v247 offset:21504
	ds_read_b128 v[184:187], v247 offset:22528
	ds_read_b128 v[188:191], v247 offset:23552
	global_load_lds_dwordx4 v[212:213], off
	s_add_i32 m0, s74, 0x2000
	v_lshl_add_u64 v[214:215], s[72:73], 0, v[204:205]
	s_add_u32 s72, s72, s2
	s_addc_u32 s73, s73, 0
	s_add_i32 s74, s75, s54
	global_load_lds_dwordx4 v[214:215], off
	v_lshl_add_u64 v[216:217], s[72:73], 0, v[192:193]
	s_mov_b32 m0, s74
	v_lshl_add_u64 v[218:219], s[72:73], 0, v[204:205]
	global_load_lds_dwordx4 v[216:217], off
	s_add_i32 m0, s74, 0x2000
	v_lshl_add_u64 v[220:221], s[4:5], 0, v[200:201]
	global_load_lds_dwordx4 v[218:219], off
	s_mov_b32 m0, s55
	v_lshl_add_u64 v[222:223], s[4:5], 0, v[202:203]
	global_load_lds_dwordx4 v[220:221], off
	s_mov_b32 m0, s56
	s_nop 0
	global_load_lds_dwordx4 v[222:223], off
	s_waitcnt lgkmcnt(0)
	s_barrier
	s_setprio 1
	s_waitcnt lgkmcnt(0)
	v_mfma_f32_16x16x32_bf16 v[60:63], v[128:131], v[160:163], v[60:63]
	v_mfma_f32_16x16x32_bf16 v[56:59], v[136:139], v[160:163], v[56:59]
	v_mfma_f32_16x16x32_bf16 v[44:47], v[128:131], v[168:171], v[44:47]
	v_mfma_f32_16x16x32_bf16 v[40:43], v[136:139], v[168:171], v[40:43]
	v_mfma_f32_16x16x32_bf16 v[28:31], v[128:131], v[176:179], v[28:31]
	v_mfma_f32_16x16x32_bf16 v[24:27], v[136:139], v[176:179], v[24:27]
	v_mfma_f32_16x16x32_bf16 v[12:15], v[128:131], v[184:187], v[12:15]
	v_mfma_f32_16x16x32_bf16 v[8:11], v[136:139], v[184:187], v[8:11]
	v_mfma_f32_16x16x32_bf16 v[60:63], v[132:135], v[164:167], v[60:63]
	v_mfma_f32_16x16x32_bf16 v[56:59], v[140:143], v[164:167], v[56:59]
	v_mfma_f32_16x16x32_bf16 v[44:47], v[132:135], v[172:175], v[44:47]
	v_mfma_f32_16x16x32_bf16 v[40:43], v[140:143], v[172:175], v[40:43]
	v_mfma_f32_16x16x32_bf16 v[28:31], v[132:135], v[180:183], v[28:31]
	v_mfma_f32_16x16x32_bf16 v[24:27], v[140:143], v[180:183], v[24:27]
	v_mfma_f32_16x16x32_bf16 v[12:15], v[132:135], v[188:191], v[12:15]
	v_mfma_f32_16x16x32_bf16 v[8:11], v[140:143], v[188:191], v[8:11]
	s_setprio 0
	s_setprio 1
	v_mfma_f32_16x16x32_bf16 v[52:55], v[144:147], v[160:163], v[52:55]
	v_mfma_f32_16x16x32_bf16 v[48:51], v[152:155], v[160:163], v[48:51]
	v_mfma_f32_16x16x32_bf16 v[36:39], v[144:147], v[168:171], v[36:39]
	v_mfma_f32_16x16x32_bf16 v[32:35], v[152:155], v[168:171], v[32:35]
	v_mfma_f32_16x16x32_bf16 v[20:23], v[144:147], v[176:179], v[20:23]
	v_mfma_f32_16x16x32_bf16 v[16:19], v[152:155], v[176:179], v[16:19]
	v_mfma_f32_16x16x32_bf16 v[4:7], v[144:147], v[184:187], v[4:7]
	v_mfma_f32_16x16x32_bf16 v[0:3], v[152:155], v[184:187], v[0:3]
	v_mfma_f32_16x16x32_bf16 v[52:55], v[148:151], v[164:167], v[52:55]
	v_mfma_f32_16x16x32_bf16 v[48:51], v[156:159], v[164:167], v[48:51]
	v_mfma_f32_16x16x32_bf16 v[36:39], v[148:151], v[172:175], v[36:39]
	v_mfma_f32_16x16x32_bf16 v[32:35], v[156:159], v[172:175], v[32:35]
	v_mfma_f32_16x16x32_bf16 v[20:23], v[148:151], v[180:183], v[20:23]
	v_mfma_f32_16x16x32_bf16 v[16:19], v[156:159], v[180:183], v[16:19]
	v_mfma_f32_16x16x32_bf16 v[4:7], v[148:151], v[188:191], v[4:7]
	v_mfma_f32_16x16x32_bf16 v[0:3], v[156:159], v[188:191], v[0:3]
	s_setprio 0
	s_waitcnt vmcnt(8)
	s_barrier
; #define PG8_STAGE(bufoff, gbase, voff) do { _Pragma("unroll") for (int _i = 0; _i < 2; ++_i) \
;         __builtin_amdgcn_global_load_lds((const unsigned*)((const char*)(gbase) + (voff)[_i]), (LAS unsigned*)(lds + (bufoff) + ldsw + _i * 8192), 16, 0, 0); } while (0)
; #define PG8_LDA(dst, b, h) do { _Pragma("unroll") for (int m = 0; m < 4; ++m) _Pragma("unroll") for (int k = 0; k < 2; ++k) dst[m][k] = *(const LAS bf16x8*)(lds + PG8_SA(b, h) + aoff + m * 2048 + k * 1024); } while (0)
; #define PG8_LDB(dst, b, h) do { _Pragma("unroll") for (int n = 0; n < 2; ++n) _Pragma("unroll") for (int k = 0; k < 2; ++k) dst[n][k] = *(const LAS bf16x8*)(lds + PG8_SB(b, h) + boff + n * 2048 + k * 1024); } while (0)
; #define PG8_MMA(ai, bj, At, Bt) do { __builtin_amdgcn_s_setprio(1); _Pragma("unroll") for (int m = 0; m < 4; ++m) _Pragma("unroll") for (int n = 0; n < 2; ++n) _Pragma("unroll") for (int k = 0; k < 2; ++k) \
;         acc[ai][bj][m][n] = __builtin_amdgcn_mfma_f32_16x16x32_bf16(Bt[n][k], At[m][k], acc[ai][bj][m][n], 0, 0, 0); __builtin_amdgcn_s_setprio(0); } while (0)
; #define PG8_WAIT_V(n) asm volatile("s_waitcnt vmcnt(" #n ")" ::: "memory")
; #define PG8_WAIT_L(n) asm volatile("s_waitcnt lgkmcnt(" #n ")" ::: "memory")
; #define PG8_BAR __builtin_amdgcn_s_barrier()
; #define PG8_SCHED __builtin_amdgcn_sched_barrier(0)
; template <class Epi>
; __device__ __forceinline__ void gemm_phase(LAS unsigned char* lds, const Gemm g, const StaticOrder& S, const Epi& E) {
;     ...
;             PG8_LDB(B0, 1, 0); PG8_LDB(B1, 1, 1); PG8_SCHED; PG8_LDA(At, 1, 0); PG8_STAGE(PG8_SA(0, 1), a2 + hstep, voffA);
;             PG8_WAIT_V(8); PG8_WAIT_L(0); PG8_BAR; PG8_MMA(0, 0, At, B0); PG8_MMA(0, 1, At, B1); PG8_BAR; PG8_SCHED;
;             PG8_LDA(At, 1, 1); PG8_STAGE(PG8_SB(1, 0), b3, voffB); PG8_STAGE(PG8_SB(1, 1), b3 + hstep, voffB); PG8_STAGE(PG8_SA(1, 0), a3, voffA);
	s_add_i32 s72, 0, 0x18000
	s_add_i32 s73, 0, 0x1c000
	v_add_u32_e32 v140, s72, v245
	v_add_u32_e32 v156, s73, v245
	ds_read_b128 v[128:131], v140
	ds_read_b128 v[132:135], v140 offset:1024
	ds_read_b128 v[136:139], v140 offset:2048
	ds_read_b128 v[140:143], v140 offset:3072
	ds_read_b128 v[144:147], v156
	ds_read_b128 v[148:151], v156 offset:1024
	ds_read_b128 v[152:155], v156 offset:2048
	ds_read_b128 v[156:159], v156 offset:3072
	s_add_u32 s4, s4, s2
	s_addc_u32 s5, s5, 0
	s_mov_b32 m0, s57
	v_lshl_add_u64 v[224:225], s[4:5], 0, v[200:201]
	ds_read_b128 v[160:163], v247 offset:32768
	ds_read_b128 v[164:167], v247 offset:33792
	ds_read_b128 v[168:171], v247 offset:34816
	ds_read_b128 v[172:175], v247 offset:35840
	ds_read_b128 v[176:179], v247 offset:36864
	ds_read_b128 v[180:183], v247 offset:37888
	ds_read_b128 v[184:187], v247 offset:38912
	ds_read_b128 v[188:191], v247 offset:39936
	global_load_lds_dwordx4 v[224:225], off
	v_lshl_add_u64 v[224:225], s[4:5], 0, v[202:203]
	s_mov_b32 m0, s58
	s_nop 0
	global_load_lds_dwordx4 v[224:225], off
	s_waitcnt lgkmcnt(0)
	s_barrier
	s_setprio 1
	s_waitcnt lgkmcnt(0)
	v_mfma_f32_16x16x32_bf16 v[124:127], v[128:131], v[160:163], v[124:127]
	v_mfma_f32_16x16x32_bf16 v[120:123], v[136:139], v[160:163], v[120:123]
	v_mfma_f32_16x16x32_bf16 v[108:111], v[128:131], v[168:171], v[108:111]
	v_mfma_f32_16x16x32_bf16 v[104:107], v[136:139], v[168:171], v[104:107]
	v_mfma_f32_16x16x32_bf16 v[92:95], v[128:131], v[176:179], v[92:95]
	v_mfma_f32_16x16x32_bf16 v[88:91], v[136:139], v[176:179], v[88:91]
	v_mfma_f32_16x16x32_bf16 v[76:79], v[128:131], v[184:187], v[76:79]
	v_mfma_f32_16x16x32_bf16 v[72:75], v[136:139], v[184:187], v[72:75]
	v_mfma_f32_16x16x32_bf16 v[124:127], v[132:135], v[164:167], v[124:127]
	v_mfma_f32_16x16x32_bf16 v[120:123], v[140:143], v[164:167], v[120:123]
	v_mfma_f32_16x16x32_bf16 v[108:111], v[132:135], v[172:175], v[108:111]
	v_mfma_f32_16x16x32_bf16 v[104:107], v[140:143], v[172:175], v[104:107]
	v_mfma_f32_16x16x32_bf16 v[92:95], v[132:135], v[180:183], v[92:95]
	v_mfma_f32_16x16x32_bf16 v[88:91], v[140:143], v[180:183], v[88:91]
	v_mfma_f32_16x16x32_bf16 v[76:79], v[132:135], v[188:191], v[76:79]
	v_mfma_f32_16x16x32_bf16 v[72:75], v[140:143], v[188:191], v[72:75]
	s_setprio 0
	s_setprio 1
	v_mfma_f32_16x16x32_bf16 v[116:119], v[144:147], v[160:163], v[116:119]
	v_mfma_f32_16x16x32_bf16 v[112:115], v[152:155], v[160:163], v[112:115]
	v_mfma_f32_16x16x32_bf16 v[100:103], v[144:147], v[168:171], v[100:103]
	v_mfma_f32_16x16x32_bf16 v[96:99], v[152:155], v[168:171], v[96:99]
	v_mfma_f32_16x16x32_bf16 v[84:87], v[144:147], v[176:179], v[84:87]
	v_mfma_f32_16x16x32_bf16 v[80:83], v[152:155], v[176:179], v[80:83]
	v_mfma_f32_16x16x32_bf16 v[68:71], v[144:147], v[184:187], v[68:71]
	v_mfma_f32_16x16x32_bf16 v[64:67], v[152:155], v[184:187], v[64:67]
	v_mfma_f32_16x16x32_bf16 v[116:119], v[148:151], v[164:167], v[116:119]
	v_mfma_f32_16x16x32_bf16 v[112:115], v[156:159], v[164:167], v[112:115]
	v_mfma_f32_16x16x32_bf16 v[100:103], v[148:151], v[172:175], v[100:103]
	v_mfma_f32_16x16x32_bf16 v[96:99], v[156:159], v[172:175], v[96:99]
	v_mfma_f32_16x16x32_bf16 v[84:87], v[148:151], v[180:183], v[84:87]
	v_mfma_f32_16x16x32_bf16 v[80:83], v[156:159], v[180:183], v[80:83]
	v_mfma_f32_16x16x32_bf16 v[68:71], v[148:151], v[188:191], v[68:71]
	v_mfma_f32_16x16x32_bf16 v[64:67], v[156:159], v[188:191], v[64:67]
	s_setprio 0
	s_waitcnt vmcnt(8)
	s_barrier
	s_add_i32 s4, s72, s54
	v_lshl_add_u64 v[212:213], v[212:213], 0, s[12:13]
	s_mov_b32 m0, s4
	ds_read_b128 v[160:163], v247 offset:49152
	ds_read_b128 v[164:167], v247 offset:50176
	ds_read_b128 v[168:171], v247 offset:51200
	ds_read_b128 v[172:175], v247 offset:52224
	ds_read_b128 v[176:179], v247 offset:53248
	ds_read_b128 v[180:183], v247 offset:54272
	ds_read_b128 v[184:187], v247 offset:55296
	ds_read_b128 v[188:191], v247 offset:56320
	global_load_lds_dwordx4 v[212:213], off
	v_lshl_add_u64 v[212:213], v[214:215], 0, s[12:13]
	s_add_i32 m0, s4, 0x2000
	s_add_i32 s4, s73, s54
	global_load_lds_dwordx4 v[212:213], off
	v_lshl_add_u64 v[212:213], v[216:217], 0, s[12:13]
	s_mov_b32 m0, s4
	s_nop 0
	global_load_lds_dwordx4 v[212:213], off
	v_lshl_add_u64 v[212:213], v[218:219], 0, s[12:13]
	s_add_i32 m0, s4, 0x2000
	s_nop 0
	global_load_lds_dwordx4 v[212:213], off
	v_lshl_add_u64 v[212:213], v[220:221], 0, s[12:13]
	s_mov_b32 m0, s59
	s_nop 0
	global_load_lds_dwordx4 v[212:213], off
	v_lshl_add_u64 v[212:213], v[222:223], 0, s[12:13]
	s_mov_b32 m0, s60
	s_nop 0
	global_load_lds_dwordx4 v[212:213], off
	s_waitcnt lgkmcnt(0)
	s_barrier
; #define PG8_STAGE(bufoff, gbase, voff) do { _Pragma("unroll") for (int _i = 0; _i < 2; ++_i) \
;         __builtin_amdgcn_global_load_lds((const unsigned*)((const char*)(gbase) + (voff)[_i]), (LAS unsigned*)(lds + (bufoff) + ldsw + _i * 8192), 16, 0, 0); } while (0)
; #define PG8_LDA(dst, b, h) do { _Pragma("unroll") for (int m = 0; m < 4; ++m) _Pragma("unroll") for (int k = 0; k < 2; ++k) dst[m][k] = *(const LAS bf16x8*)(lds + PG8_SA(b, h) + aoff + m * 2048 + k * 1024); } while (0)
; #define PG8_LDB(dst, b, h) do { _Pragma("unroll") for (int n = 0; n < 2; ++n) _Pragma("unroll") for (int k = 0; k < 2; ++k) dst[n][k] = *(const LAS bf16x8*)(lds + PG8_SB(b, h) + boff + n * 2048 + k * 1024); } while (0)
; #define PG8_MMA(ai, bj, At, Bt) do { __builtin_amdgcn_s_setprio(1); _Pragma("unroll") for (int m = 0; m < 4; ++m) _Pragma("unroll") for (int n = 0; n < 2; ++n) _Pragma("unroll") for (int k = 0; k < 2; ++k) \
;         acc[ai][bj][m][n] = __builtin_amdgcn_mfma_f32_16x16x32_bf16(Bt[n][k], At[m][k], acc[ai][bj][m][n], 0, 0, 0); __builtin_amdgcn_s_setprio(0); } while (0)
; #define PG8_WAIT_V(n) asm volatile("s_waitcnt vmcnt(" #n ")" ::: "memory")
; #define PG8_WAIT_L(n) asm volatile("s_waitcnt lgkmcnt(" #n ")" ::: "memory")
; #define PG8_BAR __builtin_amdgcn_s_barrier()
; #define PG8_SCHED __builtin_amdgcn_sched_barrier(0)
; template <class Epi>
; __device__ __forceinline__ void gemm_phase(LAS unsigned char* lds, const Gemm g, const StaticOrder& S, const Epi& E) {
;     ...
;         for (int t = 0; t < nt; t += 2) {
;             const bool last = (t == nt - 2);
;             const char* a1 = cA + (size_t)(t + 1) * kstep;
;             const char* a2 = last ? nA : cA + (size_t)(t + 2) * kstep; const char* b2 = last ? nB : cB + (size_t)(t + 2) * kstep;
;             const char* a3 = a2 + kstep; const char* b3 = b2 + kstep;
;             PG8_LDB(B0, 0, 0); PG8_LDB(B1, 0, 1); PG8_SCHED; PG8_LDA(At, 0, 0); PG8_STAGE(PG8_SA(1, 1), a1 + hstep, voffA);
;             PG8_WAIT_V(8); PG8_WAIT_L(0); PG8_BAR; PG8_MMA(0, 0, At, B0); PG8_MMA(0, 1, At, B1); PG8_BAR; PG8_SCHED;
;     ...
;             PG8_WAIT_V(8); PG8_WAIT_L(0); PG8_BAR; PG8_MMA(1, 0, At, B0); PG8_MMA(1, 1, At, B1); PG8_BAR; PG8_SCHED;
;         }
	s_setprio 1
	s_waitcnt lgkmcnt(0)
	v_mfma_f32_16x16x32_bf16 v[60:63], v[128:131], v[160:163], v[60:63]
	v_mfma_f32_16x16x32_bf16 v[56:59], v[136:139], v[160:163], v[56:59]
	v_mfma_f32_16x16x32_bf16 v[44:47], v[128:131], v[168:171], v[44:47]
	v_mfma_f32_16x16x32_bf16 v[40:43], v[136:139], v[168:171], v[40:43]
	v_mfma_f32_16x16x32_bf16 v[28:31], v[128:131], v[176:179], v[28:31]
	v_mfma_f32_16x16x32_bf16 v[24:27], v[136:139], v[176:179], v[24:27]
	v_mfma_f32_16x16x32_bf16 v[12:15], v[128:131], v[184:187], v[12:15]
	v_mfma_f32_16x16x32_bf16 v[8:11], v[136:139], v[184:187], v[8:11]
	v_mfma_f32_16x16x32_bf16 v[60:63], v[132:135], v[164:167], v[60:63]
	v_mfma_f32_16x16x32_bf16 v[56:59], v[140:143], v[164:167], v[56:59]
	v_mfma_f32_16x16x32_bf16 v[44:47], v[132:135], v[172:175], v[44:47]
	v_mfma_f32_16x16x32_bf16 v[40:43], v[140:143], v[172:175], v[40:43]
	v_mfma_f32_16x16x32_bf16 v[28:31], v[132:135], v[180:183], v[28:31]
	v_mfma_f32_16x16x32_bf16 v[24:27], v[140:143], v[180:183], v[24:27]
	v_mfma_f32_16x16x32_bf16 v[12:15], v[132:135], v[188:191], v[12:15]
	v_mfma_f32_16x16x32_bf16 v[8:11], v[140:143], v[188:191], v[8:11]
	s_setprio 0
	s_setprio 1
	v_mfma_f32_16x16x32_bf16 v[52:55], v[144:147], v[160:163], v[52:55]
	v_mfma_f32_16x16x32_bf16 v[48:51], v[152:155], v[160:163], v[48:51]
	v_mfma_f32_16x16x32_bf16 v[36:39], v[144:147], v[168:171], v[36:39]
	v_mfma_f32_16x16x32_bf16 v[32:35], v[152:155], v[168:171], v[32:35]
	v_mfma_f32_16x16x32_bf16 v[20:23], v[144:147], v[176:179], v[20:23]
	v_mfma_f32_16x16x32_bf16 v[16:19], v[152:155], v[176:179], v[16:19]
	v_mfma_f32_16x16x32_bf16 v[4:7], v[144:147], v[184:187], v[4:7]
	v_mfma_f32_16x16x32_bf16 v[0:3], v[152:155], v[184:187], v[0:3]
	v_mfma_f32_16x16x32_bf16 v[52:55], v[148:151], v[164:167], v[52:55]
	v_mfma_f32_16x16x32_bf16 v[48:51], v[156:159], v[164:167], v[48:51]
	v_mfma_f32_16x16x32_bf16 v[36:39], v[148:151], v[172:175], v[36:39]
	v_mfma_f32_16x16x32_bf16 v[32:35], v[156:159], v[172:175], v[32:35]
	v_mfma_f32_16x16x32_bf16 v[20:23], v[148:151], v[180:183], v[20:23]
	v_mfma_f32_16x16x32_bf16 v[16:19], v[156:159], v[180:183], v[16:19]
	v_mfma_f32_16x16x32_bf16 v[4:7], v[148:151], v[188:191], v[4:7]
	v_mfma_f32_16x16x32_bf16 v[0:3], v[156:159], v[188:191], v[0:3]
	s_setprio 0
	s_waitcnt vmcnt(8)
	s_barrier
	s_add_u32 s0, s0, 0x100
	s_addc_u32 s1, s1, 0
	s_add_u32 s6, s6, 0x100
	s_addc_u32 s7, s7, 0
	s_cmp_ge_u32 s71, s61
	s_mov_b32 s4, s71
	s_cbranch_scc0 .Lk_ra
	s_branch .Lk_done
.Lk_grpb:
	s_add_i32 s71, s4, 2
	s_add_u32 s72, s0, 0x80
	s_addc_u32 s5, s1, 0
	s_add_i32 s74, 0, 0x10000
	s_cmp_eq_u32 s62, s4
	s_cselect_b32 s5, s49, s5
	s_cselect_b32 s4, s48, s72
	s_cselect_b32 s73, s51, s7
	s_cselect_b32 s72, s50, s6
	s_add_i32 s75, 0, 0x14000
	v_add_u32_e32 v140, s74, v245
	v_add_u32_e32 v156, s75, v245
	ds_read_b128 v[128:131], v140
	ds_read_b128 v[132:135], v140 offset:1024
	ds_read_b128 v[136:139], v140 offset:2048
	ds_read_b128 v[140:143], v140 offset:3072
	ds_read_b128 v[144:147], v156
	ds_read_b128 v[148:151], v156 offset:1024
	ds_read_b128 v[152:155], v156 offset:2048
	ds_read_b128 v[156:159], v156 offset:3072
	v_lshl_add_u64 v[212:213], s[0:1], 0, v[208:209]
	s_add_i32 m0, s55, 0xc000
	ds_read_b128 v[160:163], v247
	ds_read_b128 v[164:167], v247 offset:1024
	ds_read_b128 v[168:171], v247 offset:2048
	ds_read_b128 v[172:175], v247 offset:3072
	ds_read_b128 v[176:179], v247 offset:4096
	ds_read_b128 v[180:183], v247 offset:5120
	ds_read_b128 v[184:187], v247 offset:6144
	ds_read_b128 v[188:191], v247 offset:7168
	global_load_lds_dwordx4 v[212:213], off
	v_lshl_add_u64 v[212:213], s[0:1], 0, v[210:211]
	s_add_i32 m0, s55, 0xe000
	s_nop 0
	global_load_lds_dwordx4 v[212:213], off
	s_waitcnt vmcnt(8)
	s_waitcnt lgkmcnt(0)
	s_barrier
	s_setprio 1
	s_waitcnt lgkmcnt(0)
	v_mfma_f32_16x16x32_bf16 v[124:127], v[128:131], v[160:163], 0
	v_mfma_f32_16x16x32_bf16 v[120:123], v[136:139], v[160:163], 0
	v_mfma_f32_16x16x32_bf16 v[108:111], v[128:131], v[168:171], 0
	v_mfma_f32_16x16x32_bf16 v[104:107], v[136:139], v[168:171], 0
	v_mfma_f32_16x16x32_bf16 v[92:95], v[128:131], v[176:179], 0
	v_mfma_f32_16x16x32_bf16 v[88:91], v[136:139], v[176:179], 0
	v_mfma_f32_16x16x32_bf16 v[76:79], v[128:131], v[184:187], 0
	v_mfma_f32_16x16x32_bf16 v[72:75], v[136:139], v[184:187], 0
	v_mfma_f32_16x16x32_bf16 v[124:127], v[132:135], v[164:167], v[124:127]
	v_mfma_f32_16x16x32_bf16 v[120:123], v[140:143], v[164:167], v[120:123]
	v_mfma_f32_16x16x32_bf16 v[108:111], v[132:135], v[172:175], v[108:111]
	v_mfma_f32_16x16x32_bf16 v[104:107], v[140:143], v[172:175], v[104:107]
	v_mfma_f32_16x16x32_bf16 v[92:95], v[132:135], v[180:183], v[92:95]
	v_mfma_f32_16x16x32_bf16 v[88:91], v[140:143], v[180:183], v[88:91]
	v_mfma_f32_16x16x32_bf16 v[76:79], v[132:135], v[188:191], v[76:79]
	v_mfma_f32_16x16x32_bf16 v[72:75], v[140:143], v[188:191], v[72:75]
	s_setprio 0
	s_setprio 1
	v_mfma_f32_16x16x32_bf16 v[116:119], v[144:147], v[160:163], 0
	v_mfma_f32_16x16x32_bf16 v[112:115], v[152:155], v[160:163], 0
	v_mfma_f32_16x16x32_bf16 v[100:103], v[144:147], v[168:171], 0
	v_mfma_f32_16x16x32_bf16 v[96:99], v[152:155], v[168:171], 0
	v_mfma_f32_16x16x32_bf16 v[84:87], v[144:147], v[176:179], 0
	v_mfma_f32_16x16x32_bf16 v[80:83], v[152:155], v[176:179], 0
	v_mfma_f32_16x16x32_bf16 v[68:71], v[144:147], v[184:187], 0
	v_mfma_f32_16x16x32_bf16 v[64:67], v[152:155], v[184:187], 0
	v_mfma_f32_16x16x32_bf16 v[116:119], v[148:151], v[164:167], v[116:119]
	v_mfma_f32_16x16x32_bf16 v[112:115], v[156:159], v[164:167], v[112:115]
	v_mfma_f32_16x16x32_bf16 v[100:103], v[148:151], v[172:175], v[100:103]
	v_mfma_f32_16x16x32_bf16 v[96:99], v[156:159], v[172:175], v[96:99]
	v_mfma_f32_16x16x32_bf16 v[84:87], v[148:151], v[180:183], v[84:87]
	v_mfma_f32_16x16x32_bf16 v[80:83], v[156:159], v[180:183], v[80:83]
	v_mfma_f32_16x16x32_bf16 v[68:71], v[148:151], v[188:191], v[68:71]
	v_mfma_f32_16x16x32_bf16 v[64:67], v[156:159], v[188:191], v[64:67]
	s_setprio 0
	s_barrier
; #define PG8_STAGE(bufoff, gbase, voff) do { _Pragma("unroll") for (int _i = 0; _i < 2; ++_i) \
;         __builtin_amdgcn_global_load_lds((const unsigned*)((const char*)(gbase) + (voff)[_i]), (LAS unsigned*)(lds + (bufoff) + ldsw + _i * 8192), 16, 0, 0); } while (0)
; #define PG8_LDA(dst, b, h) do { _Pragma("unroll") for (int m = 0; m < 4; ++m) _Pragma("unroll") for (int k = 0; k < 2; ++k) dst[m][k] = *(const LAS bf16x8*)(lds + PG8_SA(b, h) + aoff + m * 2048 + k * 1024); } while (0)
; #define PG8_LDB(dst, b, h) do { _Pragma("unroll") for (int n = 0; n < 2; ++n) _Pragma("unroll") for (int k = 0; k < 2; ++k) dst[n][k] = *(const LAS bf16x8*)(lds + PG8_SB(b, h) + boff + n * 2048 + k * 1024); } while (0)
; #define PG8_MMA(ai, bj, At, Bt) do { __builtin_amdgcn_s_setprio(1); _Pragma("unroll") for (int m = 0; m < 4; ++m) _Pragma("unroll") for (int n = 0; n < 2; ++n) _Pragma("unroll") for (int k = 0; k < 2; ++k) \
;         acc[ai][bj][m][n] = __builtin_amdgcn_mfma_f32_16x16x32_bf16(Bt[n][k], At[m][k], acc[ai][bj][m][n], 0, 0, 0); __builtin_amdgcn_s_setprio(0); } while (0)
; #define PG8_WAIT_V(n) asm volatile("s_waitcnt vmcnt(" #n ")" ::: "memory")
; #define PG8_WAIT_L(n) asm volatile("s_waitcnt lgkmcnt(" #n ")" ::: "memory")
; #define PG8_BAR __builtin_amdgcn_s_barrier()
; #define PG8_SCHED __builtin_amdgcn_sched_barrier(0)
; template <class Epi>
; __device__ __forceinline__ void gemm_phase(LAS unsigned char* lds, const Gemm g, const StaticOrder& S, const Epi& E) {
;     ...
;             PG8_LDA(At, 0, 1); PG8_STAGE(PG8_SB(0, 0), b2, voffB); PG8_STAGE(PG8_SB(0, 1), b2 + hstep, voffB); PG8_STAGE(PG8_SA(0, 0), a2, voffA);
;             PG8_WAIT_V(8); PG8_WAIT_L(0); PG8_BAR; PG8_MMA(1, 0, At, B0); PG8_MMA(1, 1, At, B1); PG8_BAR; PG8_SCHED;
;             PG8_LDB(B0, 1, 0); PG8_LDB(B1, 1, 1); PG8_SCHED; PG8_LDA(At, 1, 0); PG8_STAGE(PG8_SA(0, 1), a2 + hstep, voffA);
;             PG8_WAIT_V(8); PG8_WAIT_L(0); PG8_BAR; PG8_MMA(0, 0, At, B0); PG8_MMA(0, 1, At, B1); PG8_BAR; PG8_SCHED;
	s_add_i32 s74, s74, s54
	v_lshl_add_u64 v[212:213], s[72:73], 0, v[192:193]
	s_mov_b32 m0, s74
	ds_read_b128 v[160:163], v247 offset:16384
	ds_read_b128 v[164:167], v247 offset:17408
	ds_read_b128 v[168:171], v247 offset:18432
	ds_read_b128 v[172:175], v247 offset:19456
	ds_read_b128 v[176:179], v247 offset:20480
	ds_read_b128 v[180:183], v247 offset:21504
	ds_read_b128 v[184:187], v247 offset:22528
	ds_read_b128 v[188:191], v247 offset:23552
	global_load_lds_dwordx4 v[212:213], off
	s_add_i32 m0, s74, 0x2000
	v_lshl_add_u64 v[214:215], s[72:73], 0, v[204:205]
	s_add_u32 s72, s72, s2
	s_addc_u32 s73, s73, 0
	s_add_i32 s74, s75, s54
	global_load_lds_dwordx4 v[214:215], off
	v_lshl_add_u64 v[216:217], s[72:73], 0, v[192:193]
	s_mov_b32 m0, s74
	v_lshl_add_u64 v[218:219], s[72:73], 0, v[204:205]
	global_load_lds_dwordx4 v[216:217], off
	s_add_i32 m0, s74, 0x2000
	v_lshl_add_u64 v[220:221], s[4:5], 0, v[200:201]
	global_load_lds_dwordx4 v[218:219], off
	s_mov_b32 m0, s55
	v_lshl_add_u64 v[222:223], s[4:5], 0, v[202:203]
	global_load_lds_dwordx4 v[220:221], off
	s_mov_b32 m0, s56
	s_nop 0
	global_load_lds_dwordx4 v[222:223], off
	s_waitcnt vmcnt(8)
	s_waitcnt lgkmcnt(0)
	s_barrier
	s_setprio 1
	s_waitcnt lgkmcnt(0)
	v_mfma_f32_16x16x32_bf16 v[60:63], v[128:131], v[160:163], 0
	v_mfma_f32_16x16x32_bf16 v[56:59], v[136:139], v[160:163], 0
	v_mfma_f32_16x16x32_bf16 v[44:47], v[128:131], v[168:171], 0
	v_mfma_f32_16x16x32_bf16 v[40:43], v[136:139], v[168:171], 0
	v_mfma_f32_16x16x32_bf16 v[28:31], v[128:131], v[176:179], 0
	v_mfma_f32_16x16x32_bf16 v[24:27], v[136:139], v[176:179], 0
	v_mfma_f32_16x16x32_bf16 v[12:15], v[128:131], v[184:187], 0
	v_mfma_f32_16x16x32_bf16 v[8:11], v[136:139], v[184:187], 0
	v_mfma_f32_16x16x32_bf16 v[60:63], v[132:135], v[164:167], v[60:63]
	v_mfma_f32_16x16x32_bf16 v[56:59], v[140:143], v[164:167], v[56:59]
	v_mfma_f32_16x16x32_bf16 v[44:47], v[132:135], v[172:175], v[44:47]
	v_mfma_f32_16x16x32_bf16 v[40:43], v[140:143], v[172:175], v[40:43]
	v_mfma_f32_16x16x32_bf16 v[28:31], v[132:135], v[180:183], v[28:31]
	v_mfma_f32_16x16x32_bf16 v[24:27], v[140:143], v[180:183], v[24:27]
	v_mfma_f32_16x16x32_bf16 v[12:15], v[132:135], v[188:191], v[12:15]
	v_mfma_f32_16x16x32_bf16 v[8:11], v[140:143], v[188:191], v[8:11]
	s_setprio 0
	s_setprio 1
	v_mfma_f32_16x16x32_bf16 v[52:55], v[144:147], v[160:163], 0
	v_mfma_f32_16x16x32_bf16 v[48:51], v[152:155], v[160:163], 0
	v_mfma_f32_16x16x32_bf16 v[36:39], v[144:147], v[168:171], 0
	v_mfma_f32_16x16x32_bf16 v[32:35], v[152:155], v[168:171], 0
	v_mfma_f32_16x16x32_bf16 v[20:23], v[144:147], v[176:179], 0
	v_mfma_f32_16x16x32_bf16 v[16:19], v[152:155], v[176:179], 0
	v_mfma_f32_16x16x32_bf16 v[4:7], v[144:147], v[184:187], 0
	v_mfma_f32_16x16x32_bf16 v[0:3], v[152:155], v[184:187], 0
	v_mfma_f32_16x16x32_bf16 v[52:55], v[148:151], v[164:167], v[52:55]
	v_mfma_f32_16x16x32_bf16 v[48:51], v[156:159], v[164:167], v[48:51]
	v_mfma_f32_16x16x32_bf16 v[36:39], v[148:151], v[172:175], v[36:39]
	v_mfma_f32_16x16x32_bf16 v[32:35], v[156:159], v[172:175], v[32:35]
	v_mfma_f32_16x16x32_bf16 v[20:23], v[148:151], v[180:183], v[20:23]
	v_mfma_f32_16x16x32_bf16 v[16:19], v[156:159], v[180:183], v[16:19]
	v_mfma_f32_16x16x32_bf16 v[4:7], v[148:151], v[188:191], v[4:7]
	v_mfma_f32_16x16x32_bf16 v[0:3], v[156:159], v[188:191], v[0:3]
	s_setprio 0
	s_barrier
	s_add_i32 s72, 0, 0x18000
	s_add_i32 s73, 0, 0x1c000
	v_add_u32_e32 v140, s72, v245
	v_add_u32_e32 v156, s73, v245
	ds_read_b128 v[128:131], v140
	ds_read_b128 v[132:135], v140 offset:1024
	ds_read_b128 v[136:139], v140 offset:2048
	ds_read_b128 v[140:143], v140 offset:3072
	ds_read_b128 v[144:147], v156
	ds_read_b128 v[148:151], v156 offset:1024
	ds_read_b128 v[152:155], v156 offset:2048
	ds_read_b128 v[156:159], v156 offset:3072
	s_add_u32 s4, s4, s2
	s_addc_u32 s5, s5, 0
	s_mov_b32 m0, s57
	v_lshl_add_u64 v[224:225], s[4:5], 0, v[200:201]
	ds_read_b128 v[160:163], v247 offset:32768
	ds_read_b128 v[164:167], v247 offset:33792
	ds_read_b128 v[168:171], v247 offset:34816
	ds_read_b128 v[172:175], v247 offset:35840
	ds_read_b128 v[176:179], v247 offset:36864
	ds_read_b128 v[180:183], v247 offset:37888
	ds_read_b128 v[184:187], v247 offset:38912
	ds_read_b128 v[188:191], v247 offset:39936
	global_load_lds_dwordx4 v[224:225], off
	v_lshl_add_u64 v[224:225], s[4:5], 0, v[202:203]
	s_mov_b32 m0, s58
	s_nop 0
	global_load_lds_dwordx4 v[224:225], off
	s_waitcnt vmcnt(8)
	s_waitcnt lgkmcnt(0)
	s_barrier
; #define PG8_STAGE(bufoff, gbase, voff) do { _Pragma("unroll") for (int _i = 0; _i < 2; ++_i) \
;         __builtin_amdgcn_global_load_lds((const unsigned*)((const char*)(gbase) + (voff)[_i]), (LAS unsigned*)(lds + (bufoff) + ldsw + _i * 8192), 16, 0, 0); } while (0)
; #define PG8_LDA(dst, b, h) do { _Pragma("unroll") for (int m = 0; m < 4; ++m) _Pragma("unroll") for (int k = 0; k < 2; ++k) dst[m][k] = *(const LAS bf16x8*)(lds + PG8_SA(b, h) + aoff + m * 2048 + k * 1024); } while (0)
; #define PG8_MMA(ai, bj, At, Bt) do { __builtin_amdgcn_s_setprio(1); _Pragma("unroll") for (int m = 0; m < 4; ++m) _Pragma("unroll") for (int n = 0; n < 2; ++n) _Pragma("unroll") for (int k = 0; k < 2; ++k) \
;         acc[ai][bj][m][n] = __builtin_amdgcn_mfma_f32_16x16x32_bf16(Bt[n][k], At[m][k], acc[ai][bj][m][n], 0, 0, 0); __builtin_amdgcn_s_setprio(0); } while (0)
; #define PG8_WAIT_V(n) asm volatile("s_waitcnt vmcnt(" #n ")" ::: "memory")
; #define PG8_WAIT_L(n) asm volatile("s_waitcnt lgkmcnt(" #n ")" ::: "memory")
; #define PG8_BAR __builtin_amdgcn_s_barrier()
; #define PG8_SCHED __builtin_amdgcn_sched_barrier(0)
; template <class Epi>
; __device__ __forceinline__ void gemm_phase(LAS unsigned char* lds, const Gemm g, const StaticOrder& S, const Epi& E) {
;     ...
;             PG8_WAIT_V(8); PG8_WAIT_L(0); PG8_BAR; PG8_MMA(0, 0, At, B0); PG8_MMA(0, 1, At, B1); PG8_BAR; PG8_SCHED;
;             PG8_LDA(At, 1, 1); PG8_STAGE(PG8_SB(1, 0), b3, voffB); PG8_STAGE(PG8_SB(1, 1), b3 + hstep, voffB); PG8_STAGE(PG8_SA(1, 0), a3, voffA);
;             PG8_WAIT_V(8); PG8_WAIT_L(0); PG8_BAR; PG8_MMA(1, 0, At, B0); PG8_MMA(1, 1, At, B1); PG8_BAR; PG8_SCHED;
;         }
	s_setprio 1
	s_waitcnt lgkmcnt(0)
	v_mfma_f32_16x16x32_bf16 v[124:127], v[128:131], v[160:163], v[124:127]
	v_mfma_f32_16x16x32_bf16 v[120:123], v[136:139], v[160:163], v[120:123]
	v_mfma_f32_16x16x32_bf16 v[108:111], v[128:131], v[168:171], v[108:111]
	v_mfma_f32_16x16x32_bf16 v[104:107], v[136:139], v[168:171], v[104:107]
	v_mfma_f32_16x16x32_bf16 v[92:95], v[128:131], v[176:179], v[92:95]
	v_mfma_f32_16x16x32_bf16 v[88:91], v[136:139], v[176:179], v[88:91]
	v_mfma_f32_16x16x32_bf16 v[76:79], v[128:131], v[184:187], v[76:79]
	v_mfma_f32_16x16x32_bf16 v[72:75], v[136:139], v[184:187], v[72:75]
	v_mfma_f32_16x16x32_bf16 v[124:127], v[132:135], v[164:167], v[124:127]
	v_mfma_f32_16x16x32_bf16 v[120:123], v[140:143], v[164:167], v[120:123]
	v_mfma_f32_16x16x32_bf16 v[108:111], v[132:135], v[172:175], v[108:111]
	v_mfma_f32_16x16x32_bf16 v[104:107], v[140:143], v[172:175], v[104:107]
	v_mfma_f32_16x16x32_bf16 v[92:95], v[132:135], v[180:183], v[92:95]
	v_mfma_f32_16x16x32_bf16 v[88:91], v[140:143], v[180:183], v[88:91]
	v_mfma_f32_16x16x32_bf16 v[76:79], v[132:135], v[188:191], v[76:79]
	v_mfma_f32_16x16x32_bf16 v[72:75], v[140:143], v[188:191], v[72:75]
	s_setprio 0
	s_setprio 1
	v_mfma_f32_16x16x32_bf16 v[116:119], v[144:147], v[160:163], v[116:119]
	v_mfma_f32_16x16x32_bf16 v[112:115], v[152:155], v[160:163], v[112:115]
	v_mfma_f32_16x16x32_bf16 v[100:103], v[144:147], v[168:171], v[100:103]
	v_mfma_f32_16x16x32_bf16 v[96:99], v[152:155], v[168:171], v[96:99]
	v_mfma_f32_16x16x32_bf16 v[84:87], v[144:147], v[176:179], v[84:87]
	v_mfma_f32_16x16x32_bf16 v[80:83], v[152:155], v[176:179], v[80:83]
	v_mfma_f32_16x16x32_bf16 v[68:71], v[144:147], v[184:187], v[68:71]
	v_mfma_f32_16x16x32_bf16 v[64:67], v[152:155], v[184:187], v[64:67]
	v_mfma_f32_16x16x32_bf16 v[116:119], v[148:151], v[164:167], v[116:119]
	v_mfma_f32_16x16x32_bf16 v[112:115], v[156:159], v[164:167], v[112:115]
	v_mfma_f32_16x16x32_bf16 v[100:103], v[148:151], v[172:175], v[100:103]
	v_mfma_f32_16x16x32_bf16 v[96:99], v[156:159], v[172:175], v[96:99]
	v_mfma_f32_16x16x32_bf16 v[84:87], v[148:151], v[180:183], v[84:87]
	v_mfma_f32_16x16x32_bf16 v[80:83], v[156:159], v[180:183], v[80:83]
	v_mfma_f32_16x16x32_bf16 v[68:71], v[148:151], v[188:191], v[68:71]
	v_mfma_f32_16x16x32_bf16 v[64:67], v[156:159], v[188:191], v[64:67]
	s_setprio 0
	s_barrier
	s_add_i32 s4, s72, s54
	v_lshl_add_u64 v[212:213], v[212:213], 0, s[12:13]
	s_mov_b32 m0, s4
	ds_read_b128 v[160:163], v247 offset:49152
	ds_read_b128 v[164:167], v247 offset:50176
	ds_read_b128 v[168:171], v247 offset:51200
	ds_read_b128 v[172:175], v247 offset:52224
	ds_read_b128 v[176:179], v247 offset:53248
	ds_read_b128 v[180:183], v247 offset:54272
	ds_read_b128 v[184:187], v247 offset:55296
	ds_read_b128 v[188:191], v247 offset:56320
	global_load_lds_dwordx4 v[212:213], off
	v_lshl_add_u64 v[212:213], v[214:215], 0, s[12:13]
	s_add_i32 m0, s4, 0x2000
	s_add_i32 s4, s73, s54
	global_load_lds_dwordx4 v[212:213], off
	v_lshl_add_u64 v[212:213], v[216:217], 0, s[12:13]
	s_mov_b32 m0, s4
	s_nop 0
	global_load_lds_dwordx4 v[212:213], off
	v_lshl_add_u64 v[212:213], v[218:219], 0, s[12:13]
	s_add_i32 m0, s4, 0x2000
	s_nop 0
	global_load_lds_dwordx4 v[212:213], off
	v_lshl_add_u64 v[212:213], v[220:221], 0, s[12:13]
	s_mov_b32 m0, s59
	s_nop 0
	global_load_lds_dwordx4 v[212:213], off
	v_lshl_add_u64 v[212:213], v[222:223], 0, s[12:13]
	s_mov_b32 m0, s60
	s_nop 0
	global_load_lds_dwordx4 v[212:213], off
	s_waitcnt vmcnt(8)
	s_waitcnt lgkmcnt(0)
	s_barrier
	s_setprio 1
	s_waitcnt lgkmcnt(0)
	v_mfma_f32_16x16x32_bf16 v[60:63], v[128:131], v[160:163], v[60:63]
	v_mfma_f32_16x16x32_bf16 v[56:59], v[136:139], v[160:163], v[56:59]
	v_mfma_f32_16x16x32_bf16 v[44:47], v[128:131], v[168:171], v[44:47]
	v_mfma_f32_16x16x32_bf16 v[40:43], v[136:139], v[168:171], v[40:43]
	v_mfma_f32_16x16x32_bf16 v[28:31], v[128:131], v[176:179], v[28:31]
	v_mfma_f32_16x16x32_bf16 v[24:27], v[136:139], v[176:179], v[24:27]
	v_mfma_f32_16x16x32_bf16 v[12:15], v[128:131], v[184:187], v[12:15]
	v_mfma_f32_16x16x32_bf16 v[8:11], v[136:139], v[184:187], v[8:11]
	v_mfma_f32_16x16x32_bf16 v[60:63], v[132:135], v[164:167], v[60:63]
	v_mfma_f32_16x16x32_bf16 v[56:59], v[140:143], v[164:167], v[56:59]
	v_mfma_f32_16x16x32_bf16 v[44:47], v[132:135], v[172:175], v[44:47]
	v_mfma_f32_16x16x32_bf16 v[40:43], v[140:143], v[172:175], v[40:43]
	v_mfma_f32_16x16x32_bf16 v[28:31], v[132:135], v[180:183], v[28:31]
	v_mfma_f32_16x16x32_bf16 v[24:27], v[140:143], v[180:183], v[24:27]
	v_mfma_f32_16x16x32_bf16 v[12:15], v[132:135], v[188:191], v[12:15]
	v_mfma_f32_16x16x32_bf16 v[8:11], v[140:143], v[188:191], v[8:11]
	s_setprio 0
	s_setprio 1
	v_mfma_f32_16x16x32_bf16 v[52:55], v[144:147], v[160:163], v[52:55]
	v_mfma_f32_16x16x32_bf16 v[48:51], v[152:155], v[160:163], v[48:51]
	v_mfma_f32_16x16x32_bf16 v[36:39], v[144:147], v[168:171], v[36:39]
	v_mfma_f32_16x16x32_bf16 v[32:35], v[152:155], v[168:171], v[32:35]
	v_mfma_f32_16x16x32_bf16 v[20:23], v[144:147], v[176:179], v[20:23]
	v_mfma_f32_16x16x32_bf16 v[16:19], v[152:155], v[176:179], v[16:19]
	v_mfma_f32_16x16x32_bf16 v[4:7], v[144:147], v[184:187], v[4:7]
	v_mfma_f32_16x16x32_bf16 v[0:3], v[152:155], v[184:187], v[0:3]
	v_mfma_f32_16x16x32_bf16 v[52:55], v[148:151], v[164:167], v[52:55]
	v_mfma_f32_16x16x32_bf16 v[48:51], v[156:159], v[164:167], v[48:51]
	v_mfma_f32_16x16x32_bf16 v[36:39], v[148:151], v[172:175], v[36:39]
	v_mfma_f32_16x16x32_bf16 v[32:35], v[156:159], v[172:175], v[32:35]
	v_mfma_f32_16x16x32_bf16 v[20:23], v[148:151], v[180:183], v[20:23]
	v_mfma_f32_16x16x32_bf16 v[16:19], v[156:159], v[180:183], v[16:19]
	v_mfma_f32_16x16x32_bf16 v[4:7], v[148:151], v[188:191], v[4:7]
	v_mfma_f32_16x16x32_bf16 v[0:3], v[156:159], v[188:191], v[0:3]
	s_setprio 0
	s_barrier
	s_add_u32 s0, s0, 0x100
	s_addc_u32 s1, s1, 0
	s_add_u32 s6, s6, 0x100
	s_addc_u32 s7, s7, 0
	s_cmp_ge_u32 s71, s61
	s_mov_b32 s4, s71
	s_cbranch_scc1 .Lk_done
